# stack12 + scan-unit prologue gate scans with DPP (no ds_bpermute left in the MIX units)
# speedup vs baseline: 1.0073x; 1.0005x over previous
; #define LAS __attribute__((address_space(3)))
; __device__ __forceinline__ float lx_up(float v, int o, int lane) { return __int_as_float(__builtin_amdgcn_ds_bpermute((lane - o) << 2, __float_as_int(v))); }
; __device__ __forceinline__ float lx_get(float v, int src) { return __int_as_float(__builtin_amdgcn_readlane(__float_as_int(v), src)); }
; #define LDS_WAIT() asm volatile("s_waitcnt lgkmcnt(0)" ::: "memory")
; __device__ __forceinline__ float wave_incl_sum(float v, int lane) {
; #pragma unroll
;     for (int o = 1; o < 64; o <<= 1) { const float t = lx_up(v, o, lane); if (lane >= o) v += t; }
;     return v;
; }
; __device__ __forceinline__ float wave_incl_max(float v, int lane) {
; #pragma unroll
;     for (int o = 1; o < 64; o <<= 1) { const float t = lx_up(v, o, lane); if (lane >= o) v = fmaxf(v, t); }
;     return v;
; }
; __device__ __forceinline__ void gate_compute(const GateRaw& r, int dir, float m0, LAS float* bL, LAS float* gL, LAS float* ML, int lane, float& Gmax, float& bend) {
;     const int p0 = 2 * lane, t0 = dir ? 127 - p0 : p0, t1 = dir ? t0 - 1 : t0 + 1;
;     const float incl = wave_incl_sum(r.lf0 + r.lf1, lane), excl = incl - (r.lf0 + r.lf1);
;     const float b0 = excl + r.lf0, b1 = incl, g0 = r.li0 - b0, g1 = r.li1 - b1;
;     const float gi = wave_incl_max(fmaxf(g0, g1), lane); float ge = lx_up(gi, 1, lane); if (lane == 0) ge = -INFINITY;
;     const float G0 = fmaxf(ge, g0), G1 = gi;
;     bL[t0] = b0; bL[t1] = b1; gL[t0] = g0; gL[t1] = g1; ML[t0] = fmaxf(m0, G0); ML[t1] = fmaxf(m0, G1);
;     Gmax = lx_get(gi, 63); bend = lx_get(incl, 63);
; }
; __device__ __forceinline__ void scan_unit(unsigned char* ws, int b, int h, int dir, gu32* flag, LAS unsigned char* lds, int tid) {
;     ...
;       for (int q = 0; q < 3; ++q) { const int ci = wid + 8 * q; if (ci < NCHUNK) { float Gmax, bend; gate_compute(gr[q], dir, 0.f, tmpb, tmpb + 128, tmpb + 256, lane, Gmax, bend);
;           LDS_WAIT();
;           WKA[ci * 128 + lane] = __builtin_amdgcn_exp2f((tmpb[128 + lane] - Gmax) * LOG2E); WKA[ci * 128 + lane + 64] = __builtin_amdgcn_exp2f((tmpb[128 + lane + 64] - Gmax) * LOG2E);
;           if (lane == 0) { GMA[ci] = Gmax; BEA[ci] = bend; } LDS_WAIT(); } } }
.LBB0_247:
	s_mul_i32 s6, s18, 0x600
	s_add_i32 s6, s41, s6
	s_add_i32 s47, s6, 0x12500
	s_add_i32 s5, s41, 0x10000
	v_lshlrev_b32_e32 v4, 2, v3
	v_lshl_add_u32 v10, v0, 2, s47
	s_add_i32 s19, s41, 0x12400
	s_add_i32 s20, s41, 0x12480
	v_add_u32_e32 v5, s5, v4
	v_add_u32_e32 v8, -4, v4
	v_cmp_eq_u32_e64 s[6:7], 0, v3
	v_add_u32_e32 v21, -8, v4
	v_cmp_gt_u32_e64 s[14:15], 2, v3
	v_add_u32_e32 v20, -16, v4
	v_cmp_gt_u32_e64 s[12:13], 4, v3
	v_subrev_u32_e32 v18, 32, v4
	v_cmp_gt_u32_e64 s[10:11], 8, v3
	v_subrev_u32_e32 v17, 64, v4
	v_cmp_gt_u32_e64 s[8:9], 16, v3
	v_add_u32_e32 v16, 0xffffff80, v4
	v_cmp_gt_u32_e64 s[42:43], 32, v3
	v_lshl_add_u32 v11, s4, 2, v10
	s_andn2_b64 vcc, exec, s[44:45]
	v_add_u32_e32 v0, s47, v4
	s_cbranch_vccnz .LBB0_251
	s_waitcnt vmcnt(0)
	v_add_f32_e32 v26, v26, v19
	v_mov_b32_e32 v27, v26
	s_nop 1
	v_add_f32_dpp v27, v27, v27 row_shr:1 row_mask:0xf bank_mask:0xf
	s_nop 1
	v_add_f32_dpp v27, v27, v27 row_shr:2 row_mask:0xf bank_mask:0xf
	s_nop 1
	v_add_f32_dpp v27, v27, v27 row_shr:4 row_mask:0xf bank_mask:0xf
	s_nop 1
	v_add_f32_dpp v27, v27, v27 row_shr:8 row_mask:0xf bank_mask:0xf
	s_nop 1
	v_add_f32_dpp v27, v27, v27 row_bcast:15 row_mask:0xa bank_mask:0xf
	s_nop 1
	v_add_f32_dpp v27, v27, v27 row_bcast:31 row_mask:0xc bank_mask:0xf
	v_sub_f32_e32 v26, v27, v26
	v_add_f32_e32 v19, v19, v26
	v_sub_f32_e32 v24, v24, v27
	v_sub_f32_e32 v15, v15, v19
	v_max_f32_e32 v26, v15, v24
	ds_write2st64_b32 v11, v27, v24 offset1:2
	ds_write2st64_b32 v10, v19, v15 offset1:2
	v_readlane_b32 s45, v27, 63
	s_nop 1
	v_max_f32_dpp v26, v26, v26 row_shr:1 row_mask:0xf bank_mask:0xf
	s_nop 1
	v_max_f32_dpp v26, v26, v26 row_shr:2 row_mask:0xf bank_mask:0xf
	s_nop 1
	v_max_f32_dpp v26, v26, v26 row_shr:4 row_mask:0xf bank_mask:0xf
	s_nop 1
	v_max_f32_dpp v26, v26, v26 row_shr:8 row_mask:0xf bank_mask:0xf
	s_nop 1
	v_max_f32_dpp v26, v26, v26 row_bcast:15 row_mask:0xa bank_mask:0xf
	s_nop 1
	v_max_f32_dpp v26, v26, v26 row_bcast:31 row_mask:0xc bank_mask:0xf
	v_mov_b32_e32 v28, v243
	s_nop 1
	v_mov_b32_dpp v28, v26 wave_shr:1 row_mask:0xf bank_mask:0xf
	v_max_f32_e32 v19, v26, v26
	v_max_f32_e32 v19, 0, v19
	v_readlane_b32 s44, v26, 63
	s_nop 0
	v_mov_b32_e32 v24, v28
	v_max3_f32 v15, v24, v15, 0
	ds_write_b32 v10, v15 offset:1024
	ds_write_b32 v11, v19 offset:1024
	s_waitcnt lgkmcnt(0)
	ds_read_b32 v15, v0 offset:512
	v_lshl_add_u32 v19, s18, 9, v5
	s_waitcnt lgkmcnt(0)
	v_subrev_f32_e32 v15, s44, v15
	v_mul_f32_e32 v15, 0x3fb8aa3b, v15
	v_exp_f32_e32 v15, v15
	ds_write_b32 v19, v15
	ds_read_b32 v15, v0 offset:768
	s_waitcnt lgkmcnt(0)
	v_subrev_f32_e32 v15, s44, v15
	v_mul_f32_e32 v15, 0x3fb8aa3b, v15
	v_exp_f32_e32 v15, v15
	ds_write_b32 v19, v15 offset:256
	s_and_saveexec_b64 s[4:5], s[6:7]
	s_cbranch_execz .LBB0_250
	s_lshl_b32 s47, s18, 2
	s_add_i32 s48, s20, s47
	s_add_i32 s47, s19, s47
	v_mov_b32_e32 v15, s47
	v_mov_b32_e32 v19, s44
	ds_write_b32 v15, v19
	v_mov_b32_e32 v15, s48
	v_mov_b32_e32 v19, s45
	ds_write_b32 v15, v19

; #define LAS __attribute__((address_space(3)))
; __device__ __forceinline__ float lx_up(float v, int o, int lane) { return __int_as_float(__builtin_amdgcn_ds_bpermute((lane - o) << 2, __float_as_int(v))); }
; __device__ __forceinline__ float lx_get(float v, int src) { return __int_as_float(__builtin_amdgcn_readlane(__float_as_int(v), src)); }
; #define LDS_WAIT() asm volatile("s_waitcnt lgkmcnt(0)" ::: "memory")
; __device__ __forceinline__ float wave_incl_sum(float v, int lane) {
; #pragma unroll
;     for (int o = 1; o < 64; o <<= 1) { const float t = lx_up(v, o, lane); if (lane >= o) v += t; }
;     return v;
; }
; __device__ __forceinline__ float wave_incl_max(float v, int lane) {
; #pragma unroll
;     for (int o = 1; o < 64; o <<= 1) { const float t = lx_up(v, o, lane); if (lane >= o) v = fmaxf(v, t); }
;     return v;
; }
; __device__ __forceinline__ void gate_compute(const GateRaw& r, int dir, float m0, LAS float* bL, LAS float* gL, LAS float* ML, int lane, float& Gmax, float& bend) {
;     const int p0 = 2 * lane, t0 = dir ? 127 - p0 : p0, t1 = dir ? t0 - 1 : t0 + 1;
;     const float incl = wave_incl_sum(r.lf0 + r.lf1, lane), excl = incl - (r.lf0 + r.lf1);
;     const float b0 = excl + r.lf0, b1 = incl, g0 = r.li0 - b0, g1 = r.li1 - b1;
;     const float gi = wave_incl_max(fmaxf(g0, g1), lane); float ge = lx_up(gi, 1, lane); if (lane == 0) ge = -INFINITY;
;     const float G0 = fmaxf(ge, g0), G1 = gi;
;     bL[t0] = b0; bL[t1] = b1; gL[t0] = g0; gL[t1] = g1; ML[t0] = fmaxf(m0, G0); ML[t1] = fmaxf(m0, G1);
;     Gmax = lx_get(gi, 63); bend = lx_get(incl, 63);
; }
; __device__ __forceinline__ void scan_unit(unsigned char* ws, int b, int h, int dir, gu32* flag, LAS unsigned char* lds, int tid) {
;     ...
;       for (int q = 0; q < 3; ++q) { const int ci = wid + 8 * q; if (ci < NCHUNK) { float Gmax, bend; gate_compute(gr[q], dir, 0.f, tmpb, tmpb + 128, tmpb + 256, lane, Gmax, bend);
;           LDS_WAIT();
;           WKA[ci * 128 + lane] = __builtin_amdgcn_exp2f((tmpb[128 + lane] - Gmax) * LOG2E); WKA[ci * 128 + lane + 64] = __builtin_amdgcn_exp2f((tmpb[128 + lane + 64] - Gmax) * LOG2E);
;           if (lane == 0) { GMA[ci] = Gmax; BEA[ci] = bend; } LDS_WAIT(); } } }
.LBB0_251:
	s_andn2_b64 vcc, exec, s[38:39]
	s_cbranch_vccnz .LBB0_255
	s_waitcnt vmcnt(0)
	v_add_f32_e32 v15, v25, v14
	v_mov_b32_e32 v19, v15
	s_nop 1
	v_add_f32_dpp v19, v19, v19 row_shr:1 row_mask:0xf bank_mask:0xf
	s_nop 1
	v_add_f32_dpp v19, v19, v19 row_shr:2 row_mask:0xf bank_mask:0xf
	s_nop 1
	v_add_f32_dpp v19, v19, v19 row_shr:4 row_mask:0xf bank_mask:0xf
	s_nop 1
	v_add_f32_dpp v19, v19, v19 row_shr:8 row_mask:0xf bank_mask:0xf
	s_nop 1
	v_add_f32_dpp v19, v19, v19 row_bcast:15 row_mask:0xa bank_mask:0xf
	s_nop 1
	v_add_f32_dpp v19, v19, v19 row_bcast:31 row_mask:0xc bank_mask:0xf
	v_sub_f32_e32 v15, v19, v15
	v_add_f32_e32 v14, v14, v15
	v_sub_f32_e32 v23, v23, v19
	v_sub_f32_e32 v12, v12, v14
	v_max_f32_e32 v15, v12, v23
	ds_write2st64_b32 v11, v19, v23 offset1:2
	ds_write2st64_b32 v10, v14, v12 offset1:2
	v_readlane_b32 s39, v19, 63
	s_nop 1
	v_max_f32_dpp v15, v15, v15 row_shr:1 row_mask:0xf bank_mask:0xf
	s_nop 1
	v_max_f32_dpp v15, v15, v15 row_shr:2 row_mask:0xf bank_mask:0xf
	s_nop 1
	v_max_f32_dpp v15, v15, v15 row_shr:4 row_mask:0xf bank_mask:0xf
	s_nop 1
	v_max_f32_dpp v15, v15, v15 row_shr:8 row_mask:0xf bank_mask:0xf
	s_nop 1
	v_max_f32_dpp v15, v15, v15 row_bcast:15 row_mask:0xa bank_mask:0xf
	s_nop 1
	v_max_f32_dpp v15, v15, v15 row_bcast:31 row_mask:0xc bank_mask:0xf
	v_mov_b32_e32 v24, v243
	s_nop 1
	v_mov_b32_dpp v24, v15 wave_shr:1 row_mask:0xf bank_mask:0xf
	v_max_f32_e32 v14, v15, v15
	v_max_f32_e32 v14, 0, v14
	v_readlane_b32 s38, v15, 63
	s_nop 0
	v_mov_b32_e32 v23, v24
	v_max3_f32 v12, v23, v12, 0
	ds_write_b32 v10, v12 offset:1024
	ds_write_b32 v11, v14 offset:1024
	s_waitcnt lgkmcnt(0)
	ds_read_b32 v12, v0 offset:512
	v_lshl_add_u32 v14, s17, 9, v5
	s_waitcnt lgkmcnt(0)
	v_subrev_f32_e32 v12, s38, v12
	v_mul_f32_e32 v12, 0x3fb8aa3b, v12
	v_exp_f32_e32 v12, v12
	ds_write_b32 v14, v12
	ds_read_b32 v12, v0 offset:768
	s_waitcnt lgkmcnt(0)
	v_subrev_f32_e32 v12, s38, v12
	v_mul_f32_e32 v12, 0x3fb8aa3b, v12
	v_exp_f32_e32 v12, v12
	ds_write_b32 v14, v12 offset:256
	s_and_saveexec_b64 s[4:5], s[6:7]
	s_cbranch_execz .LBB0_254
	s_lshl_b32 s17, s17, 2
	s_add_i32 s44, s20, s17
	s_add_i32 s17, s19, s17
	v_mov_b32_e32 v12, s17
	v_mov_b32_e32 v14, s38
	ds_write_b32 v12, v14
	v_mov_b32_e32 v12, s44
	v_mov_b32_e32 v14, s39
	ds_write_b32 v12, v14

; #define LAS __attribute__((address_space(3)))
; __device__ __forceinline__ float lx_up(float v, int o, int lane) { return __int_as_float(__builtin_amdgcn_ds_bpermute((lane - o) << 2, __float_as_int(v))); }
; __device__ __forceinline__ float lx_get(float v, int src) { return __int_as_float(__builtin_amdgcn_readlane(__float_as_int(v), src)); }
; #define LDS_WAIT() asm volatile("s_waitcnt lgkmcnt(0)" ::: "memory")
; __device__ __forceinline__ float wave_incl_sum(float v, int lane) {
; #pragma unroll
;     for (int o = 1; o < 64; o <<= 1) { const float t = lx_up(v, o, lane); if (lane >= o) v += t; }
;     return v;
; }
; __device__ __forceinline__ float wave_incl_max(float v, int lane) {
; #pragma unroll
;     for (int o = 1; o < 64; o <<= 1) { const float t = lx_up(v, o, lane); if (lane >= o) v = fmaxf(v, t); }
;     return v;
; }
; __device__ __forceinline__ void gate_compute(const GateRaw& r, int dir, float m0, LAS float* bL, LAS float* gL, LAS float* ML, int lane, float& Gmax, float& bend) {
;     const int p0 = 2 * lane, t0 = dir ? 127 - p0 : p0, t1 = dir ? t0 - 1 : t0 + 1;
;     const float incl = wave_incl_sum(r.lf0 + r.lf1, lane), excl = incl - (r.lf0 + r.lf1);
;     const float b0 = excl + r.lf0, b1 = incl, g0 = r.li0 - b0, g1 = r.li1 - b1;
;     const float gi = wave_incl_max(fmaxf(g0, g1), lane); float ge = lx_up(gi, 1, lane); if (lane == 0) ge = -INFINITY;
;     const float G0 = fmaxf(ge, g0), G1 = gi;
;     bL[t0] = b0; bL[t1] = b1; gL[t0] = g0; gL[t1] = g1; ML[t0] = fmaxf(m0, G0); ML[t1] = fmaxf(m0, G1);
;     Gmax = lx_get(gi, 63); bend = lx_get(incl, 63);
; }
; __device__ __forceinline__ void scan_unit(unsigned char* ws, int b, int h, int dir, gu32* flag, LAS unsigned char* lds, int tid) {
;     ...
;       for (int q = 0; q < 3; ++q) { const int ci = wid + 8 * q; if (ci < NCHUNK) { float Gmax, bend; gate_compute(gr[q], dir, 0.f, tmpb, tmpb + 128, tmpb + 256, lane, Gmax, bend);
;           LDS_WAIT();
;           WKA[ci * 128 + lane] = __builtin_amdgcn_exp2f((tmpb[128 + lane] - Gmax) * LOG2E); WKA[ci * 128 + lane + 64] = __builtin_amdgcn_exp2f((tmpb[128 + lane + 64] - Gmax) * LOG2E);
;           if (lane == 0) { GMA[ci] = Gmax; BEA[ci] = bend; } LDS_WAIT(); } } }
.LBB0_255:
	s_waitcnt vmcnt(3)
	v_cndmask_b32_e64 v12, 0, 1, s[2:3]
	v_cmp_ne_u32_e64 s[4:5], 1, v12
	s_andn2_b64 vcc, exec, s[2:3]
	s_mov_b64 s[38:39], 0
	s_cbranch_vccnz .LBB0_259
	s_waitcnt vmcnt(0)
	v_add_f32_e32 v12, v22, v9
	v_lshl_add_u32 v5, s16, 9, v5
	v_mov_b32_e32 v14, v12
	s_nop 1
	v_add_f32_dpp v14, v14, v14 row_shr:1 row_mask:0xf bank_mask:0xf
	s_nop 1
	v_add_f32_dpp v14, v14, v14 row_shr:2 row_mask:0xf bank_mask:0xf
	s_nop 1
	v_add_f32_dpp v14, v14, v14 row_shr:4 row_mask:0xf bank_mask:0xf
	s_nop 1
	v_add_f32_dpp v14, v14, v14 row_shr:8 row_mask:0xf bank_mask:0xf
	s_nop 1
	v_add_f32_dpp v14, v14, v14 row_bcast:15 row_mask:0xa bank_mask:0xf
	s_nop 1
	v_add_f32_dpp v14, v14, v14 row_bcast:31 row_mask:0xc bank_mask:0xf
	v_sub_f32_e32 v12, v14, v12
	v_add_f32_e32 v9, v9, v12
	v_sub_f32_e32 v13, v13, v14
	v_sub_f32_e32 v7, v7, v9
	v_max_f32_e32 v12, v7, v13
	ds_write2st64_b32 v11, v14, v13 offset1:2
	ds_write2st64_b32 v10, v9, v7 offset1:2
	v_readlane_b32 s11, v14, 63
	s_nop 1
	v_max_f32_dpp v12, v12, v12 row_shr:1 row_mask:0xf bank_mask:0xf
	s_nop 1
	v_max_f32_dpp v12, v12, v12 row_shr:2 row_mask:0xf bank_mask:0xf
	s_nop 1
	v_max_f32_dpp v12, v12, v12 row_shr:4 row_mask:0xf bank_mask:0xf
	s_nop 1
	v_max_f32_dpp v12, v12, v12 row_shr:8 row_mask:0xf bank_mask:0xf
	s_nop 1
	v_max_f32_dpp v12, v12, v12 row_bcast:15 row_mask:0xa bank_mask:0xf
	s_nop 1
	v_max_f32_dpp v12, v12, v12 row_bcast:31 row_mask:0xc bank_mask:0xf
	v_mov_b32_e32 v8, v243
	s_nop 1
	v_mov_b32_dpp v8, v12 wave_shr:1 row_mask:0xf bank_mask:0xf
	v_max_f32_e32 v9, v12, v12
	v_max_f32_e32 v9, 0, v9
	v_readlane_b32 s10, v12, 63
	s_nop 0
	v_mov_b32_e32 v8, v8
	v_max3_f32 v7, v8, v7, 0
	ds_write_b32 v10, v7 offset:1024
	ds_write_b32 v11, v9 offset:1024
	s_waitcnt lgkmcnt(0)
	ds_read_b32 v7, v0 offset:512
	s_waitcnt lgkmcnt(0)
	v_subrev_f32_e32 v7, s10, v7
	v_mul_f32_e32 v7, 0x3fb8aa3b, v7
	v_exp_f32_e32 v7, v7
	ds_write_b32 v5, v7
	ds_read_b32 v0, v0 offset:768
	s_waitcnt lgkmcnt(0)
	v_subrev_f32_e32 v0, s10, v0
	v_mul_f32_e32 v0, 0x3fb8aa3b, v0
	v_exp_f32_e32 v0, v0
	ds_write_b32 v5, v0 offset:256
	s_and_saveexec_b64 s[8:9], s[6:7]
	s_cbranch_execz .LBB0_258
	s_lshl_b32 s12, s16, 2
	s_add_i32 s13, s20, s12
	s_add_i32 s12, s19, s12
	v_mov_b32_e32 v0, s12
	v_mov_b32_e32 v5, s10
	ds_write_b32 v0, v5
	v_mov_b32_e32 v0, s13
	v_mov_b32_e32 v5, s11
	ds_write_b32 v0, v5
